# GLA publish: decay-product loads issued before the state stores (one write-through round trip instead of two on the publish path)
# baseline (speedup 1.0000x reference)
; #define LAS __attribute__((address_space(3)))
; template <bool FULL>
; __device__ __forceinline__ void gla_pass(const Params& P, LAS unsigned char* lds, f32x4 (&S)[8][2], int bh, int c0, int L, bool dry) {
;     ...
;         for (int kt = 0; kt < 8; ++kt) { const f32x4 dv = *(const LAS f32x4*)(Ldec + 16 * kt + 4 * g); S[kt][0] = S[kt][0] * dv; S[kt][1] = S[kt][1] * dv; }
; #pragma unroll
;         for (int k2 = 0; k2 < 2; ++k2)
; #pragma unroll
;             for (int kt = 0; kt < 8; ++kt) { const bf16x8 ak = trfrag(Lks, KS_P, 32 * k2, 32 * kt, g, fr);
;                 S[kt][0] = __builtin_amdgcn_mfma_f32_16x16x32_bf16(ak, vf[0][k2], S[kt][0], 0, 0, 0); S[kt][1] = __builtin_amdgcn_mfma_f32_16x16x32_bf16(ak, vf[1][k2], S[kt][1], 0, 0, 0); }
; __device__ __forceinline__ void gla_scan(const Params& P, LAS unsigned char* lds, int bh, int seg, int nseg, bool dry) {
;     ...
;         char* dst = (char*)(SL + (size_t)(bh * 3 + seg) * 32768);
.LBB0_668:
	v_add_u32_e32 v100, 0x25000, v121
	s_waitcnt vmcnt(3)
	ds_read_b128 v[32:35], v100
	ds_read_b64_tr_b16 v[30:31], v116 offset:38016
	ds_read_b64_tr_b16 v[28:29], v116 offset:35840
	ds_read_b64_tr_b16 v[22:23], v116 offset:38048
	ds_read_b64_tr_b16 v[20:21], v116 offset:35872
	s_waitcnt vmcnt(2)
	ds_read_b128 v[40:43], v100 offset:64
	s_waitcnt vmcnt(0)
	ds_read_b64_tr_b16 v[50:51], v115 offset:1152
	ds_read_b64_tr_b16 v[48:49], v115
	s_waitcnt lgkmcnt(7)
	v_pk_mul_f32 v[46:47], v[90:91], v[34:35]
	v_pk_mul_f32 v[44:45], v[88:89], v[32:33]
	v_pk_mul_f32 v[34:35], v[86:87], v[34:35]
	ds_read_b64_tr_b16 v[52:53], v115 offset:32
	ds_read_b64_tr_b16 v[86:87], v115 offset:64
	ds_read_b64_tr_b16 v[90:91], v115 offset:96
	ds_read_b64_tr_b16 v[54:55], v115 offset:1184
	ds_read_b64_tr_b16 v[88:89], v115 offset:1216
	ds_read_b64_tr_b16 v[92:93], v115 offset:1248
	v_pk_mul_f32 v[32:33], v[84:85], v[32:33]
	s_waitcnt lgkmcnt(6)
	v_mfma_f32_16x16x32_bf16 v[44:47], v[48:51], v[28:31], v[44:47]
	v_mul_f32_e64 v82, v82, v42
	v_mul_f32_e64 v83, v83, v43
	v_pk_mul_f32 v[80:81], v[80:81], v[40:41]
	v_pk_mul_f32 v[42:43], v[78:79], v[42:43]
	v_mfma_f32_16x16x32_bf16 v[32:35], v[48:51], v[20:23], v[32:35]
	ds_read_b128 v[48:51], v100 offset:128
	v_pk_mul_f32 v[40:41], v[76:77], v[40:41]
	s_mul_i32 s4, s1, 3
	s_waitcnt lgkmcnt(3)
	v_mfma_f32_16x16x32_bf16 v[76:79], v[52:55], v[28:31], v[80:83]
	s_add_i32 s4, s4, s3
	s_lshl_b32 s4, s4, 17
	s_add_u32 s4, s18, s4
	ds_read_b128 v[80:83], v100 offset:192
	s_waitcnt lgkmcnt(1)
	v_pk_mul_f32 v[74:75], v[74:75], v[50:51]
	v_pk_mul_f32 v[72:73], v[72:73], v[48:49]
	v_mfma_f32_16x16x32_bf16 v[40:43], v[52:55], v[20:23], v[40:43]
	v_mul_f32_e64 v50, v70, v50
	v_mul_f32_e64 v51, v71, v51
	v_pk_mul_f32 v[48:49], v[68:69], v[48:49]
	s_waitcnt lgkmcnt(0)
	v_pk_mul_f32 v[54:55], v[66:67], v[82:83]
	v_mfma_f32_16x16x32_bf16 v[66:69], v[86:89], v[28:31], v[72:75]
	v_mul_f32_e64 v52, v64, v80
	v_mul_f32_e64 v53, v65, v81
	v_pk_mul_f32 v[58:59], v[58:59], v[82:83]
	v_pk_mul_f32 v[56:57], v[56:57], v[80:81]
	ds_read_b128 v[70:73], v100 offset:256
	ds_read_b128 v[80:83], v100 offset:320
	v_mfma_f32_16x16x32_bf16 v[48:51], v[86:89], v[20:23], v[48:51]
	ds_read_b64_tr_b16 v[84:85], v115 offset:128
	ds_read_b64_tr_b16 v[86:87], v115 offset:1280
	s_addc_u32 s5, s19, 0
	s_waitcnt lgkmcnt(3)
	v_pk_mul_f32 v[62:63], v[62:63], v[72:73]
	v_mfma_f32_16x16x32_bf16 v[52:55], v[90:93], v[28:31], v[52:55]
	v_mul_f32_e64 v60, v60, v70
	v_mul_f32_e64 v61, v61, v71
	v_pk_mul_f32 v[38:39], v[38:39], v[72:73]
	v_pk_mul_f32 v[36:37], v[36:37], v[70:71]
	v_mfma_f32_16x16x32_bf16 v[56:59], v[90:93], v[20:23], v[56:59]
	ds_read_b64_tr_b16 v[88:89], v115 offset:160
	ds_read_b64_tr_b16 v[92:93], v115 offset:192
	ds_read_b64_tr_b16 v[96:97], v115 offset:224
	ds_read_b64_tr_b16 v[90:91], v115 offset:1312
	ds_read_b64_tr_b16 v[94:95], v115 offset:1344
	ds_read_b64_tr_b16 v[98:99], v115 offset:1376
	s_waitcnt lgkmcnt(8)
	v_pk_mul_f32 v[26:27], v[26:27], v[82:83]
	v_pk_mul_f32 v[24:25], v[24:25], v[80:81]
	ds_read_b128 v[70:73], v100 offset:384
	v_pk_mul_f32 v[18:19], v[18:19], v[82:83]
	v_pk_mul_f32 v[16:17], v[16:17], v[80:81]
	ds_read_b128 v[80:83], v100 offset:448
	s_waitcnt lgkmcnt(8)
	v_mfma_f32_16x16x32_bf16 v[60:63], v[84:87], v[28:31], v[60:63]
	s_waitcnt lgkmcnt(1)
	v_pk_mul_f32 v[14:15], v[14:15], v[72:73]
	v_pk_mul_f32 v[12:13], v[12:13], v[70:71]
	v_pk_mul_f32 v[10:11], v[10:11], v[72:73]
	s_waitcnt lgkmcnt(0)
	v_pk_mul_f32 v[6:7], v[6:7], v[82:83]
	v_pk_mul_f32 v[4:5], v[4:5], v[80:81]
	v_mfma_f32_16x16x32_bf16 v[36:39], v[84:87], v[20:23], v[36:39]
	v_mul_f32_e64 v8, v8, v70
	v_mul_f32_e64 v9, v9, v71
	v_pk_mul_f32 v[2:3], v[2:3], v[82:83]
	v_pk_mul_f32 v[0:1], v[0:1], v[80:81]
	v_mfma_f32_16x16x32_bf16 v[24:27], v[88:91], v[28:31], v[24:27]
	s_mov_b32 s9, 0
	v_cmp_gt_i32_e32 vcc, 32, v114
	v_mfma_f32_16x16x32_bf16 v[16:19], v[88:91], v[20:23], v[16:19]
	ds_read_b64_tr_b16 v[84:85], v116 offset:53248
	ds_read_b64_tr_b16 v[86:87], v116 offset:55424
	ds_read_b64_tr_b16 v[90:91], v116 offset:55456
	ds_read_b64_tr_b16 v[88:89], v116 offset:53280
	v_mfma_f32_16x16x32_bf16 v[12:15], v[92:95], v[28:31], v[12:15]
	v_mfma_f32_16x16x32_bf16 v[4:7], v[96:99], v[28:31], v[4:7]
	ds_read_b64_tr_b16 v[28:29], v115 offset:9216
	ds_read_b64_tr_b16 v[30:31], v115 offset:10368
	v_mfma_f32_16x16x32_bf16 v[8:11], v[92:95], v[20:23], v[8:11]
	v_mfma_f32_16x16x32_bf16 v[0:3], v[96:99], v[20:23], v[0:3]
	ds_read_b64_tr_b16 v[20:21], v115 offset:9248
	ds_read_b64_tr_b16 v[70:71], v115 offset:9280
	ds_read_b64_tr_b16 v[80:81], v115 offset:9312
	ds_read_b64_tr_b16 v[22:23], v115 offset:10400
	ds_read_b64_tr_b16 v[72:73], v115 offset:10432
	ds_read_b64_tr_b16 v[82:83], v115 offset:10464
	s_waitcnt lgkmcnt(6)
	v_mfma_f32_16x16x32_bf16 v[44:47], v[28:31], v[84:87], v[44:47]
	v_mfma_f32_16x16x32_bf16 v[28:31], v[28:31], v[88:91], v[32:35]
	s_waitcnt lgkmcnt(2)
	v_mfma_f32_16x16x32_bf16 v[32:35], v[20:23], v[84:87], v[76:79]
	v_mfma_f32_16x16x32_bf16 v[20:23], v[20:23], v[88:91], v[40:43]
	s_waitcnt lgkmcnt(1)
	v_mfma_f32_16x16x32_bf16 v[40:43], v[70:73], v[84:87], v[66:69]
	ds_read_b64_tr_b16 v[64:65], v115 offset:9344
	s_nop 1
	ds_read_b64_tr_b16 v[66:67], v115 offset:10496
	s_waitcnt lgkmcnt(0)
	v_mfma_f32_16x16x32_bf16 v[60:63], v[64:67], v[84:87], v[60:63]
	v_mfma_f32_16x16x32_bf16 v[36:39], v[64:67], v[88:91], v[36:39]
	v_lshlrev_b32_e32 v64, 4, v114
	v_mfma_f32_16x16x32_bf16 v[48:51], v[70:73], v[88:91], v[48:51]
	ds_read_b64_tr_b16 v[68:69], v115 offset:9376
	ds_read_b64_tr_b16 v[72:73], v115 offset:9408
	ds_read_b64_tr_b16 v[76:77], v115 offset:9440
	ds_read_b64_tr_b16 v[70:71], v115 offset:10528
	ds_read_b64_tr_b16 v[74:75], v115 offset:10560
	ds_read_b64_tr_b16 v[78:79], v115 offset:10592
	s_waitcnt lgkmcnt(0)
	s_barrier
; __device__ __forceinline__ void gla_scan(const Params& P, LAS unsigned char* lds, int bh, int seg, int nseg, bool dry) {
;     ...
;         char* dst = (char*)(SL + (size_t)(bh * 3 + seg) * 32768);
; #pragma unroll
;         for (int kt = 0; kt < 8; ++kt)
; #pragma unroll
;             for (int vt = 0; vt < 2; ++vt) *(f32x4*)(dst + (size_t)((unsigned)tid * 16u + (unsigned)((kt * 2 + vt) * 8192))) = S[kt][vt];
;         if (tid < 32) {
;             f32x4 dc = (f32x4){1.f, 1.f, 1.f, 1.f};
;             for (int n = c0; n < c0 + L; ++n) dc = dc * *(const f32x4*)(DEC + (size_t)(bh * 64 + n) * 128 + 4 * tid);
;             *(f32x4*)(DL + (size_t)(bh * 4 + seg) * 128 + 4 * tid) = dc;
;         }
	s_barrier
	s_and_saveexec_b64 s[10:11], vcc
	s_cbranch_execz .Lpub_nold
	v_lshlrev_b32_e32 v180, 2, v114
	v_ashrrev_i32_e32 v181, 31, v180
	s_or_b32 s8, s0, s22
	v_lshlrev_b64 v[184:185], 2, v[180:181]
	s_lshl_b32 s8, s8, 9
	s_mov_b32 s12, 0x1000
	v_lshl_add_u64 v[180:181], s[50:51], 0, v[184:185]
	s_mov_b32 s13, 0
	v_lshl_add_u64 v[180:181], v[180:181], 0, s[8:9]
	s_nop 0
	v_lshl_add_u64 v[182:183], v[180:181], 0, s[12:13]
	global_load_dwordx4 v[116:119], v[180:181], off
	global_load_dwordx4 v[120:123], v[180:181], off offset:512
	global_load_dwordx4 v[124:127], v[180:181], off offset:1024
	global_load_dwordx4 v[128:131], v[180:181], off offset:1536
	global_load_dwordx4 v[132:135], v[180:181], off offset:2048
	global_load_dwordx4 v[136:139], v[180:181], off offset:2560
	global_load_dwordx4 v[140:143], v[180:181], off offset:3072
	global_load_dwordx4 v[144:147], v[180:181], off offset:3584
	global_load_dwordx4 v[148:151], v[182:183], off
	global_load_dwordx4 v[152:155], v[182:183], off offset:512
	global_load_dwordx4 v[156:159], v[182:183], off offset:1024
	global_load_dwordx4 v[160:163], v[182:183], off offset:1536
	global_load_dwordx4 v[164:167], v[182:183], off offset:2048
	global_load_dwordx4 v[168:171], v[182:183], off offset:2560
	global_load_dwordx4 v[172:175], v[182:183], off offset:3072
	global_load_dwordx4 v[176:179], v[182:183], off offset:3584
.Lpub_nold:
	s_or_b64 exec, exec, s[10:11]
	global_store_dwordx4 v64, v[44:47], s[4:5] sc1
	v_mfma_f32_16x16x32_bf16 v[52:55], v[80:83], v[84:87], v[52:55]
	s_nop 0
	v_add_u32_e32 v44, 0x2000, v64
	global_store_dwordx4 v44, v[28:31], s[4:5] sc1
	v_mfma_f32_16x16x32_bf16 v[56:59], v[80:83], v[88:91], v[56:59]
	s_nop 0
	v_add_u32_e32 v28, 0x4000, v64
	global_store_dwordx4 v28, v[32:35], s[4:5] sc1
	v_add_u32_e32 v28, 0x6000, v64
	global_store_dwordx4 v28, v[20:23], s[4:5] sc1
	v_mfma_f32_16x16x32_bf16 v[24:27], v[68:71], v[84:87], v[24:27]
	s_nop 0
	v_add_u32_e32 v20, 0x8000, v64
	global_store_dwordx4 v20, v[40:43], s[4:5] sc1
	v_add_u32_e32 v20, 0xa000, v64
	global_store_dwordx4 v20, v[48:51], s[4:5] sc1
	v_add_u32_e32 v20, 0xc000, v64
	global_store_dwordx4 v20, v[52:55], s[4:5] sc1
	v_add_u32_e32 v20, 0xe000, v64
	v_mfma_f32_16x16x32_bf16 v[16:19], v[68:71], v[88:91], v[16:19]
	global_store_dwordx4 v20, v[56:59], s[4:5] sc1
	v_add_u32_e32 v20, 0x10000, v64
	global_store_dwordx4 v20, v[60:63], s[4:5] sc1
	v_mfma_f32_16x16x32_bf16 v[12:15], v[72:75], v[84:87], v[12:15]
	v_add_u32_e32 v20, 0x12000, v64
	global_store_dwordx4 v20, v[36:39], s[4:5] sc1
	v_add_u32_e32 v20, 0x14000, v64
	v_mfma_f32_16x16x32_bf16 v[8:11], v[72:75], v[88:91], v[8:11]
	global_store_dwordx4 v20, v[24:27], s[4:5] sc1
	v_add_u32_e32 v20, 0x16000, v64
	global_store_dwordx4 v20, v[16:19], s[4:5] sc1
	v_mfma_f32_16x16x32_bf16 v[4:7], v[76:79], v[84:87], v[4:7]
	s_nop 0
	v_add_u32_e32 v16, 0x18000, v64
	global_store_dwordx4 v16, v[12:15], s[4:5] sc1
	v_mfma_f32_16x16x32_bf16 v[0:3], v[76:79], v[88:91], v[0:3]
	s_nop 0
	v_add_u32_e32 v12, 0x1a000, v64
	global_store_dwordx4 v12, v[8:11], s[4:5] sc1
	s_nop 1
	v_add_u32_e32 v8, 0x1c000, v64
	global_store_dwordx4 v8, v[4:7], s[4:5] sc1
	s_nop 1
	v_add_u32_e32 v4, 0x1e000, v64
	global_store_dwordx4 v4, v[0:3], s[4:5] sc1
	s_and_saveexec_b64 s[4:5], vcc
	s_cbranch_execz .LBB0_670
	s_lshl_b32 s8, s1, 11
	s_lshl_b32 s9, s3, 9
	s_or_b32 s8, s8, s9
	s_add_u32 s8, s6, s8
	s_addc_u32 s9, s7, 0
	s_waitcnt vmcnt(30)
	v_pk_mul_f32 v[118:119], v[118:119], v[122:123]
	v_pk_mul_f32 v[116:117], v[116:117], v[120:121]
	s_waitcnt vmcnt(29)
	v_pk_mul_f32 v[118:119], v[118:119], v[126:127]
	v_pk_mul_f32 v[116:117], v[116:117], v[124:125]
	s_waitcnt vmcnt(28)
	v_pk_mul_f32 v[118:119], v[118:119], v[130:131]
	v_pk_mul_f32 v[116:117], v[116:117], v[128:129]
	s_waitcnt vmcnt(27)
	v_pk_mul_f32 v[118:119], v[118:119], v[134:135]
	v_pk_mul_f32 v[116:117], v[116:117], v[132:133]
	s_waitcnt vmcnt(26)
	v_pk_mul_f32 v[118:119], v[118:119], v[138:139]
	v_pk_mul_f32 v[116:117], v[116:117], v[136:137]
	s_waitcnt vmcnt(25)
	v_pk_mul_f32 v[118:119], v[118:119], v[142:143]
	v_pk_mul_f32 v[116:117], v[116:117], v[140:141]
	s_waitcnt vmcnt(24)
	v_pk_mul_f32 v[118:119], v[118:119], v[146:147]
	v_pk_mul_f32 v[116:117], v[116:117], v[144:145]
	s_waitcnt vmcnt(23)
	v_pk_mul_f32 v[118:119], v[118:119], v[150:151]
	v_pk_mul_f32 v[116:117], v[116:117], v[148:149]
	s_waitcnt vmcnt(22)
	v_pk_mul_f32 v[118:119], v[118:119], v[154:155]
	v_pk_mul_f32 v[116:117], v[116:117], v[152:153]
	s_waitcnt vmcnt(21)
	v_pk_mul_f32 v[118:119], v[118:119], v[158:159]
	v_pk_mul_f32 v[116:117], v[116:117], v[156:157]
	s_waitcnt vmcnt(20)
	v_pk_mul_f32 v[118:119], v[118:119], v[162:163]
	v_pk_mul_f32 v[116:117], v[116:117], v[160:161]
	s_waitcnt vmcnt(19)
	v_pk_mul_f32 v[118:119], v[118:119], v[166:167]
	v_pk_mul_f32 v[116:117], v[116:117], v[164:165]
	s_waitcnt vmcnt(18)
	v_pk_mul_f32 v[118:119], v[118:119], v[170:171]
	v_pk_mul_f32 v[116:117], v[116:117], v[168:169]
	s_waitcnt vmcnt(17)
	v_pk_mul_f32 v[118:119], v[118:119], v[174:175]
	v_pk_mul_f32 v[116:117], v[116:117], v[172:173]
	s_waitcnt vmcnt(16)
	v_pk_mul_f32 v[118:119], v[118:119], v[178:179]
	v_pk_mul_f32 v[116:117], v[116:117], v[176:177]
	v_lshl_add_u64 v[186:187], s[8:9], 0, v[184:185]
	global_store_dwordx4 v[186:187], v[116:119], off sc1
